# grid sync split: arrival at kernel start, wait after the first phase; first phase to in-projection GEMM dependency carried by one more hierarchical XCD barrier instance
# speedup vs baseline: 1.0096x; 1.0073x over previous
; #define PG8_LAS __attribute__((address_space(3)))
; __device__ __forceinline__ void phase_weights(const Args& a, PG8_LAS float* tile, int lo, int NTILES, int bid, int nb) {
;     const int tid = threadIdx.x;
;     int it = lo + bid; if (it >= NTILES) return;
;     TileDesc cur = tile_desc(a, it); float v[16]; tile_load(cur, v);
; __global__ void __launch_bounds__(NT) mega(Args a) {
;     ...
;     if (threadIdx.x < 4) xst[threadIdx.x] = 0u;
;     __syncthreads();
;     if (blockIdx.x == 0) { unsigned* bw = (unsigned*)(a.ws + WS_BAR); for (int i = threadIdx.x; i < XCD_BAR_WORDS; i += NT) bw[i] = 0u; }
;     bf16_t* WinT = (bf16_t*)(a.ws + WS_WIN); bf16_t* WoutT = (bf16_t*)(a.ws + WS_WOUT); bf16_t* WupT = (bf16_t*)(a.ws + WS_WUP); bf16_t* WdownT = (bf16_t*)(a.ws + WS_WDOWN);
;     bf16_t* h1b = (bf16_t*)a.out; bf16_t* proj = (bf16_t*)(a.ws + WS_PROJ); bf16_t* mix = (bf16_t*)(a.ws + WS_MIX); bf16_t* xb = (bf16_t*)(a.ws + WS_XB);
;     bf16_t* uph = (bf16_t*)(a.ws + WS_UPH); bf16_t* act = (bf16_t*)(a.ws + WS_ACT); float* ss2 = (float*)(a.ws + WS_SS2);
;     const unsigned mk = a.mask;
;     if (mk & 1u) { phase_weights(a, (PG8_LAS float*)lds, 0, TW_B, (int)blockIdx.x, (int)gridDim.x); }
;     __syncthreads();
;     if (mk & 2048u) phase_norm1(a, (float*)lds_raw);
;     grid.sync();
.LBB0_10:
	s_waitcnt vmcnt(0)
	s_barrier
	v_cmp_eq_u32_e32 vcc, 0, v152
	s_and_saveexec_b64 s[4:5], vcc
	s_cbranch_execz .Lcga_end
	buffer_wbl2 sc1
	s_waitcnt vmcnt(0)
	s_load_dwordx2 s[8:9], s[2:3], 0x58
	v_mov_b32_e32 v6, 0
	s_waitcnt lgkmcnt(0)
	global_load_dword v4, v6, s[8:9] offset:40
	v_mov_b32_e32 v7, 1
	global_atomic_add v7, v6, v7, s[8:9] offset:32 sc0
	s_waitcnt vmcnt(0)
	v_add_u32_e32 v6, -1, v4
	s_nop 0
	v_cmp_eq_u32_sdwa s[10:11], v7, v6 src0_sel:WORD_0 src1_sel:DWORD
	s_and_saveexec_b64 s[6:7], s[10:11]
	s_cbranch_execz .Lcga_nl
	v_sub_u32_e32 v4, 0x10000, v4
	v_mov_b32_e32 v6, 0
	global_atomic_add v6, v4, s[8:9] offset:32
.Lcga_nl:
	s_or_b64 exec, exec, s[6:7]
	s_nop 1
	v_readfirstlane_b32 s6, v7
	v_writelane_b32 v252, s6, 59
	v_writelane_b32 v252, s8, 60
	v_writelane_b32 v252, s9, 61
.Lcga_end:
	s_or_b64 exec, exec, s[4:5]
	s_bitcmp0_b32 s18, 0
	s_cselect_b64 s[4:5], -1, 0
	s_cmpk_gt_i32 s82, 0x147
	s_cselect_b64 s[6:7], -1, 0
	s_or_b64 s[4:5], s[6:7], s[4:5]
	s_and_b64 vcc, exec, s[4:5]
	v_writelane_b32 v253, s18, 17
	s_cbranch_vccnz .LBB0_28
	s_cmpk_gt_i32 s82, 0x13f
	s_cbranch_scc0 .LBB0_14
	s_load_dwordx16 s[36:51], s[0:1], 0x0
	s_add_u32 s4, s16, 0x1c00000
	s_addc_u32 s5, s17, 0
	s_lshl_b32 s7, s82, 6
	s_and_b32 s6, s7, 0x7f80
	s_addk_i32 s6, 0xb000
	s_and_b32 s24, s7, 64
	s_mov_b64 s[8:9], 0
	s_waitcnt lgkmcnt(0)
	s_mov_b64 s[12:13], s[50:51]
	s_cbranch_execz .LBB0_15
	s_movk_i32 s25, 0x200
	s_mov_b64 s[10:11], 0x80
	s_mov_b32 s14, s24
	s_branch .LBB0_16

; __global__ void __launch_bounds__(NT) mega(Args a) {
;     ...
;     __syncthreads();
;     if (mk & 2048u) phase_norm1(a, (float*)lds_raw);
;     grid.sync();
;     XcdBarrier xbar = xcd_barrier_post((unsigned*)(a.ws + WS_BAR), xst);
;     if (mk & 2u)
;     { pg8::Gemm g{h1b, WinT, M, NPROJ, D}; pg8::StaticOrder S; S.init(M, NPROJ, (int)gridDim.x, (int)blockIdx.x); EpiBf16Plain E{proj, NPROJ, (const float*)(a.ws + WS_RS1)};
;       pg8::gemm_phase<EpiBf16Plain, pg8::StaticOrder, true, true>(lds, g, S, E); }
;     xcd_barrier(xbar);
.LBB0_44:
	v_lshrrev_b32_e32 v1, 20, v0
	v_lshrrev_b32_e32 v0, 10, v0
	v_or_b32_e32 v0, v0, v1
	s_movk_i32 s4, 0x3ff
	v_and_or_b32 v0, v0, s4, v152
	v_cmp_eq_u32_e32 vcc, 0, v0
	s_waitcnt lgkmcnt(0)
	s_barrier
	s_and_saveexec_b64 s[4:5], vcc
	s_cbranch_execz .LBB0_54
	v_readlane_b32 s6, v252, 59
	v_readlane_b32 s2, v252, 60
	v_readlane_b32 s3, v252, 61
	s_and_b32 s6, s6, 0xffff0000
	v_mov_b32_e32 v0, 0
	s_nop 4
.Lcgw_spin:
	global_load_dword v2, v0, s[2:3] offset:32 sc1
	s_waitcnt vmcnt(0)
	v_and_b32_e32 v2, 0xffff0000, v2
	v_cmp_ne_u32_e32 vcc, s6, v2
	s_cbranch_vccnz .Lcgw_done
	s_sleep 1
	s_branch .Lcgw_spin
.Lcgw_done:
.LBB0_54:
	s_or_b64 exec, exec, s[4:5]
	s_load_dwordx16 s[36:51], s[0:1], 0x40
	s_add_u32 s0, s16, 0x1e00000
	s_addc_u32 s1, s17, 0
	s_barrier
	s_waitcnt lgkmcnt(0)
	v_writelane_b32 v253, s36, 18
	v_cmp_eq_u32_e64 s[2:3], 0, v152
	s_nop 0
	v_writelane_b32 v253, s37, 19
	v_writelane_b32 v253, s38, 20
	v_writelane_b32 v253, s39, 21
	v_writelane_b32 v253, s40, 22
	v_writelane_b32 v253, s41, 23
	v_writelane_b32 v253, s42, 24
	v_writelane_b32 v253, s43, 25
	v_writelane_b32 v253, s44, 26
	v_writelane_b32 v253, s45, 27
	v_writelane_b32 v253, s46, 28
	v_writelane_b32 v253, s47, 29
	v_writelane_b32 v253, s48, 30
	v_writelane_b32 v253, s49, 31
	v_writelane_b32 v253, s50, 32
	v_writelane_b32 v253, s51, 33
	v_writelane_b32 v253, s0, 34
	s_nop 1
	v_writelane_b32 v253, s1, 35
	s_getreg_b32 s0, hwreg(HW_REG_XCC_ID, 0, 4)
	s_and_b32 s0, s0, 15
	v_writelane_b32 v253, s0, 36
	s_mov_b64 s[0:1], exec
	v_writelane_b32 v253, s2, 37
	s_nop 1
	v_writelane_b32 v253, s3, 38
	s_and_b64 s[2:3], s[0:1], s[2:3]
	s_mov_b64 exec, s[2:3]
	s_cbranch_execz .LBB0_57
	s_mov_b64 s[2:3], exec
	v_mbcnt_lo_u32_b32 v0, s2, 0
	v_mbcnt_hi_u32_b32 v0, s3, v0
	v_cmp_eq_u32_e32 vcc, 0, v0
	s_and_b64 s[4:5], exec, vcc
	s_mov_b64 exec, s[4:5]
	s_cbranch_execz .LBB0_57
	v_readlane_b32 s4, v253, 36
	s_bcnt1_i32_b64 s2, s[2:3]
	s_lshl_b32 s4, s4, 8
	v_mov_b32_e32 v1, s2
	v_readlane_b32 s2, v253, 34
	v_mov_b32_e32 v0, s4
	v_readlane_b32 s3, v253, 35
	s_nop 4
	global_atomic_add v0, v1, s[2:3] offset:1024
.LBB0_57:
	s_or_b64 exec, exec, s[0:1]
.Lxc_74:
	s_waitcnt vmcnt(0)
	s_barrier
	s_mov_b64 s[0:1], exec
	v_readlane_b32 s4, v253, 37
	v_readlane_b32 s5, v253, 38
	s_and_b64 s[4:5], s[0:1], s[4:5]
	s_mov_b64 exec, s[4:5]
	s_cbranch_execz .Lxc_126
	s_add_i32 s4, 0, 0x20000
	v_mov_b32_e32 v0, s4
	s_waitcnt vmcnt(0) expcnt(0) lgkmcnt(0)
	ds_read_b32 v2, v0
	s_add_i32 s4, 0, 0x20004
	v_mov_b32_e32 v0, s4
	ds_read_b32 v0, v0
	s_waitcnt lgkmcnt(1)
	v_cmp_ne_u32_e32 vcc, 0, v2
	s_cbranch_vccnz .Lxc_90
	v_readlane_b32 s4, v253, 0
	s_mul_i32 s33, s81, s4
	s_add_u32 s4, s16, 0x1e00200
	s_addc_u32 s5, s17, 0
	s_add_u32 s6, s16, 0x1e00400
	s_addc_u32 s7, s17, 0
	s_add_u32 s8, s16, 0x1e00500
	s_addc_u32 s9, s17, 0
	s_add_u32 s10, s16, 0x1e00600
	s_addc_u32 s11, s17, 0
	s_add_u32 s12, s16, 0x1e00700
	s_addc_u32 s13, s17, 0
	s_add_u32 s14, s16, 0x1e00800
	s_addc_u32 s15, s17, 0
	s_add_u32 s18, s16, 0x1e00900
	s_addc_u32 s19, s17, 0
	s_add_u32 s20, s16, 0x1e00a00
	s_addc_u32 s21, s17, 0
	s_add_u32 s22, s16, 0x1e00b00
	s_addc_u32 s23, s17, 0
	s_add_u32 s24, s16, 0x1e00c00
	s_addc_u32 s25, s17, 0
	s_add_u32 s26, s16, 0x1e00d00
	s_addc_u32 s27, s17, 0
	s_add_u32 s28, s16, 0x1e00e00
	s_addc_u32 s29, s17, 0
	s_add_u32 s30, s16, 0x1e00f00
	s_addc_u32 s31, s17, 0
	s_add_u32 s34, s16, 0x1e01000
	s_addc_u32 s35, s17, 0
	s_add_u32 s36, s16, 0x1e01100
	s_addc_u32 s37, s17, 0
	s_add_u32 s38, s16, 0x1e01200
	s_addc_u32 s39, s17, 0
	s_add_u32 s40, s16, 0x1e01300
	s_mul_i32 s33, s33, s80
	s_addc_u32 s41, s17, 0
	s_mov_b32 s48, 1
	v_mov_b32_e32 v16, 0
	s_branch .Lxc_78

; #define PG8_STAGE(bufoff, gbase, voff) do { _Pragma("unroll") for (int _i = 0; _i < 2; ++_i) \
;         __builtin_amdgcn_global_load_lds((const unsigned*)((const char*)(gbase) + (voff)[_i]), (PG8_LAS unsigned*)(lds + (bufoff) + ldsw + _i * 8192), 16, 0, 0); } while (0)
; #define PG8_WAIT_V(n) asm volatile("s_waitcnt vmcnt(" #n ")" ::: "memory")
; #define PG8_BAR __builtin_amdgcn_s_barrier()
;     __host__ __device__ bool next(int i, Unit& u) const {
;         const long L = (long)i * G + c; if (L >= nwg) return false;
;         int wgid = (int)L; { const int q = nwg / NXCD, r = nwg % NXCD, xcd = wgid % NXCD, off = wgid / NXCD; wgid = (xcd < r ? xcd * (q + 1) : r * (q + 1) + (xcd - r) * q) + off; }
;         const int nig = WGM * nN, gid = wgid / nig, fm = gid * WGM, gsz = (nM - fm) < WGM ? (nM - fm) : WGM;
;         u.pm = fm + ((wgid % nig) % gsz); u.pn = (wgid % nig) / gsz; return true;
; template <class Epi, class Sched, bool ALIGN_EPI = false, bool SP2 = false>
; __device__ __forceinline__ void gemm_phase(PG8_LAS unsigned char* lds, const Gemm g, const Sched& S, const Epi& E) {
;     ...
;     const char* cA = (const char*)g.A + (size_t)cur.pm * tstep; const char* cB = (const char*)g.Bt + (size_t)cur.pn * tstep;
;     S.a_ready(cur);
;     if constexpr (SP2) {
;         PG8_STAGE(PG8_SB(0, 0), cB, voffB); PG8_STAGE(PG8_SB(0, 1), cB + hstep, voffB); PG8_STAGE(PG8_SA(0, 0), cA, voffA); PG8_STAGE(PG8_SA(0, 1), cA + hstep, voffA);
;         if (wr == 1) PG8_BAR;
;         PG8_WAIT_V(2); PG8_BAR;
;         PG8_STAGE(PG8_SB(1, 0), cB + kstep, voffB); PG8_STAGE(PG8_SA(1, 0), cA + kstep, voffA); PG8_STAGE(PG8_SB(1, 1), cB + hstep + kstep, voffB);
;         PG8_WAIT_V(6); PG8_BAR;
;     } else {
;         PG8_STAGE(PG8_SB(0, 0), cB, voffB); PG8_STAGE(PG8_SA(0, 0), cA, voffA); PG8_STAGE(PG8_SB(0, 1), cB + hstep, voffB); PG8_STAGE(PG8_SA(0, 1), cA + hstep, voffA);
.Lxc_126:
	s_or_b64 exec, exec, s[0:1]
	v_readlane_b32 s0, v253, 17
	s_bitcmp0_b32 s0, 2
	v_lshrrev_b32_e32 v153, 6, v152
	s_waitcnt lgkmcnt(0)
	s_barrier
	s_add_u32 s2, s16, 0x6000000
	s_addc_u32 s3, s17, 0
	v_readlane_b32 s0, v253, 17
	s_bitcmp0_b32 s0, 1
	s_cbranch_scc1 .LBB0_74
	s_cmpk_gt_i32 s82, 0x4ff
	v_readfirstlane_b32 s1, v152
	s_cbranch_scc1 .LBB0_74
	v_lshrrev_b32_e32 v0, 5, v152
	v_lshrrev_b32_e32 v2, 1, v152
	v_and_b32_e32 v0, 4, v0
	v_bfe_u32 v1, v152, 2, 2
	s_waitcnt vmcnt(10)
	v_and_b32_e32 v11, 24, v2
	v_or3_b32 v0, v0, v1, v11
	v_lshlrev_b32_e32 v1, 4, v152
	v_add_u32_e32 v8, 0x2000, v1
	v_lshrrev_b32_e32 v2, 7, v8
	s_movk_i32 s0, 0xe0
	v_and_b32_e32 v4, 32, v152
	v_and_or_b32 v3, v2, s0, v0
	v_bitop3_b32 v9, v1, v4, 48 bitop3:0x6c
	v_and_b32_e32 v10, 64, v152
	v_bfe_u32 v12, v152, 2, 4
	s_movk_i32 s0, 0xf0
	v_or_b32_e32 v1, v9, v10
	v_and_or_b32 v2, v2, s0, v12
	v_lshl_or_b32 v130, v2, 11, v1
	v_lshrrev_b32_e32 v2, 3, v152
	s_movk_i32 s0, 0x60
	v_and_or_b32 v0, v2, s0, v0
	s_movk_i32 s0, 0x70
	s_ashr_i32 s31, s82, 31
	v_lshl_or_b32 v132, v0, 11, v1
	v_and_or_b32 v0, v2, s0, v12
	s_lshr_b32 s0, s31, 29
	s_add_i32 s0, s82, s0
	s_lshr_b32 s8, s1, 6
	s_ashr_i32 s4, s0, 3
	s_and_b32 s0, s0, -8
	s_lshr_b32 s10, s1, 8
	s_lshl_b32 s30, s8, 10
	s_sub_i32 s0, s82, s0
	s_cmp_lt_i32 s0, 0
	s_movk_i32 s33, 0xa1
	s_cselect_b32 s5, s33, 0xa0
	s_mul_i32 s0, s0, s5
	s_add_i32 s0, s0, s4
	s_mul_hi_i32 s4, s0, 0x66666667
	s_lshr_b32 s5, s4, 31
	s_ashr_i32 s4, s4, 5
	s_add_i32 s4, s4, s5
	s_lshl_b32 s5, s4, 3
	s_mulk_i32 s4, 0x50
	s_sub_i32 s4, s0, s4
	s_bfe_i32 s0, s4, 0x80000
	s_bfe_u32 s0, s0, 0x3000c
	s_add_i32 s6, s4, s0
	s_bfe_i32 s0, s6, 0x80000
	s_and_b32 s6, s6, 0xf8
	s_sub_i32 s4, s4, s6
	s_sext_i32_i16 s0, s0
	s_sext_i32_i8 s4, s4
	s_lshr_b32 s0, s0, 3
	s_add_i32 s22, s5, s4
	s_ashr_i32 s23, s22, 31
	s_bfe_i64 s[6:7], s[0:1], 0x100000
	s_lshl_b64 s[4:5], s[22:23], 19
	s_lshl_b64 s[6:7], s[6:7], 19
	s_add_u32 s26, s16, s6
	s_addc_u32 s27, s17, s7
	s_add_i32 s23, s30, 0
	s_add_i32 m0, s23, 0x10000
	v_lshl_or_b32 v128, v3, 11, v1
	global_load_lds_dwordx4 v132, s[26:27]
	s_add_i32 m0, s23, 0x12000
	s_add_u32 s6, s26, 0x40000
	global_load_lds_dwordx4 v128, s[26:27]
	s_addc_u32 s7, s27, 0
	s_add_i32 m0, s23, 0x14000
	v_lshl_or_b32 v134, v0, 11, v1
	global_load_lds_dwordx4 v132, s[6:7]
	s_add_i32 m0, s23, 0x16000
	s_add_u32 s24, s78, s4
	s_addc_u32 s25, s79, s5
	s_add_i32 s34, s23, 0x2000
	global_load_lds_dwordx4 v128, s[6:7]
	s_mov_b32 m0, s23
	s_add_u32 s4, s24, 0x40000
	global_load_lds_dwordx4 v134, s[24:25]
	s_mov_b32 m0, s34
	s_addc_u32 s5, s25, 0
	s_add_i32 s35, s23, 0x4000
	global_load_lds_dwordx4 v130, s[24:25]
	s_mov_b32 m0, s35
	s_add_i32 s36, s23, 0x6000
	global_load_lds_dwordx4 v134, s[4:5]
	s_mov_b32 m0, s36
	v_mov_b32_e32 v133, 0
	global_load_lds_dwordx4 v130, s[4:5]
	v_mov_b32_e32 v129, v133
	v_mov_b32_e32 v135, v133
	v_mov_b32_e32 v131, v133
	s_cmp_eq_u32 s10, 1
	s_mov_b32 s37, 0
	v_lshl_add_u64 v[6:7], s[26:27], 0, v[132:133]
	v_lshl_add_u64 v[4:5], s[26:27], 0, v[128:129]
	v_lshl_add_u64 v[0:1], s[24:25], 0, v[134:135]
	s_cselect_b64 s[4:5], -1, 0
	s_cmp_lg_u32 s10, 1
	v_lshl_add_u64 v[2:3], s[24:25], 0, v[130:131]
	s_cbranch_scc1 .LBB0_61
	s_barrier
